# plus: phase-0 weight conversion split: only in-proj weights before barrier 1; the other weight transposes run on workgroups 64..255 during the sixth in-proj round
# speedup vs baseline: 1.0985x; 1.0016x over previous
; #define LAS __attribute__((address_space(3)))
; #define GAS __attribute__((address_space(1)))
; template <int MODE> __device__ __forceinline__ void phase0(KP P, LAS unsigned char* lds, int gw, int NGW, int wave, int lane) {
;     GAS unsigned char* ws = ((GAS unsigned char*)P->ws);
;     LAS float* scr = (LAS float*)(lds + wave * 16384);
;     constexpr int I1 = 16 * 168, I2 = 8 * 32, I4 = 16 * 32, I5 = 16 * 176, I6 = 44 * 32, I7 = 16 * 32, I8 = 4 * 32;
;     constexpr int NIT = I1 + 2 * I2 + I4 + I5 + I6 + I7 + I8;
;     if (MODE & 5) for (int it = ((MODE & 1) ? 0 : I1) + gw; it < ((MODE & 4) ? NIT : I1); it += NGW) {
;         int r = it;
;         if (r < I1) { const int kb = r / 168, grp = r % 168, pn = grp >> 3, g = grp & 7; int src0;
;             if (pn < 4) src0 = ((pn < 2) ? 0 : 512) + 64 * (4 * (pn & 1) + (g & 3)) + 32 * (g >> 2);
;             else if (pn < 8) src0 = 1024 + 256 * (pn - 4) + 32 * g;
;             else if (pn == 8) src0 = (g < 2) ? 2048 + 32 * g : 2112;
;             else if (pn < 13) src0 = (g < 4) ? 2120 + 128 * (pn - 9) + 32 * g : 2632 + 128 * (pn - 9) + 32 * (g - 4);
;             else src0 = 3144 + 256 * (pn - 13) + 32 * g;
;             tr_item(((const GAS float*)P->in[3]), INW, 64 * kb, src0, (GAS f16*)(ws + WS_W1T), 1024, 32 * grp, nullptr, scr, lane); continue; } r -= I1;
.LBB0_5:
	s_or_b64 exec, exec, s[8:9]
	s_mov_b64 s[14:15], s[0:1]
	v_mbcnt_lo_u32_b32 v18, -1, 0
	v_mbcnt_hi_u32_b32 v18, -1, v18
	s_load_dwordx2 s[12:13], s[14:15], 0xa8
	v_readfirstlane_b32 s93, v204
	s_lshr_b32 s84, s93, 6
	s_lshl_b32 s3, s2, 3
	v_writelane_b32 v248, s3, 2
	s_add_i32 s3, s84, s3
	s_lshl_b32 s62, s30, 3
	s_movk_i32 s100, 0x217f
	s_cmpk_lg_u32 s30, 0x100
	s_cbranch_scc1 .Lp0_b1
	s_movk_i32 s100, 0xa7f
.Lp0_b1:
	s_mov_b32 s101, 0
	s_cmp_gt_i32 s3, s100
	s_cbranch_scc1 .LBB0_61
.Lp0_reenter:
	s_lshl_b32 s4, s84, 14
	s_add_i32 s8, s4, 0
	v_ashrrev_i32_e32 v1, 5, v18
	v_and_b32_e32 v2, 31, v18
	v_and_b32_e32 v3, 7, v18
	s_movk_i32 s4, 0x84
	v_mov_b32_e32 v11, 0
	v_lshlrev_b32_e32 v4, 2, v2
	v_mul_lo_u32 v5, v1, s4
	v_lshlrev_b32_e32 v10, 4, v3
	v_add3_u32 v13, s8, v4, v5
	s_waitcnt lgkmcnt(0)
	v_lshl_add_u64 v[4:5], s[12:13], 0, v[10:11]
	s_mov_b64 s[4:5], 0x2400000
	v_lshl_add_u64 v[14:15], v[4:5], 0, s[4:5]
	s_mov_b64 s[4:5], 0x1c00000
	v_lshl_add_u64 v[16:17], v[4:5], 0, s[4:5]
	s_mov_b64 s[4:5], 0xf00000
	v_lshl_add_u64 v[20:21], v[4:5], 0, s[4:5]
	s_mov_b64 s[4:5], 0xe00000
	v_lshl_add_u64 v[22:23], v[4:5], 0, s[4:5]
	s_mov_b64 s[4:5], 0xd00000
	v_ashrrev_i32_e32 v19, 3, v18
	v_lshl_add_u64 v[24:25], v[4:5], 0, s[4:5]
	s_mov_b64 s[4:5], 0x200000
	v_lshlrev_b32_e32 v12, 3, v3
	v_mul_u32_u24_e32 v6, 0x420, v3
	v_lshlrev_b32_e32 v3, 2, v19
	v_lshl_add_u64 v[26:27], v[4:5], 0, s[4:5]
	s_mov_b64 s[4:5], 0x2200000
	v_add3_u32 v41, s8, v6, v3
	v_lshl_add_u64 v[28:29], v[4:5], 0, s[4:5]
	s_mov_b64 s[4:5], 0x1100000
	s_lshl_b32 s8, s3, 1
	s_mov_b32 s17, 0
	v_add_u32_e32 v42, 8, v19
	v_add_u32_e32 v43, 16, v19
	v_add_u32_e32 v44, 24, v19
	v_lshl_add_u64 v[30:31], v[4:5], 0, s[4:5]
	s_lshl_b32 s4, s3, 5
	s_lshl_b32 s5, s62, 5
	s_add_i32 s18, s8, 0x7fffbe00
	s_lshl_b32 s19, s62, 1
	s_movk_i32 s20, 0x2000
	s_movk_i32 s21, 0x4000
	s_movk_i32 s22, 0x6000
	s_mov_b32 s23, 0x8000
	s_mov_b32 s24, 0xa000
	s_mov_b32 s25, 0xc000
	s_mov_b32 s26, 0xe000
	s_mov_b32 s27, 0x10000
	s_mov_b32 s33, 0x12000
	s_mov_b32 s34, 0x14000
	s_mov_b32 s35, 0x16000
	s_mov_b32 s38, 0x18000
	s_mov_b32 s39, 0x1a000
	s_mov_b32 s40, 0x1c000
	s_mov_b32 s41, 0x1e000
	s_mov_b32 s42, 0x20000
	s_mov_b32 s43, 0x22000
	s_mov_b32 s44, 0x24000
	s_mov_b32 s45, 0x26000
	s_mov_b32 s46, 0x28000
	s_mov_b32 s47, 0x2a000
	s_mov_b32 s48, 0x2c000
	s_mov_b32 s49, 0x2e000
	s_mov_b32 s50, 0x30000
	s_mov_b32 s51, 0x32000
	s_mov_b32 s52, 0x34000
	s_mov_b32 s53, 0x36000
	s_mov_b32 s54, 0x38000
	s_mov_b32 s55, 0x3a000
	s_mov_b32 s56, 0x3c000
	s_mov_b32 s57, 0x3e000
	s_movk_i32 s58, 0x1600
	s_movk_i32 s59, 0x70
	s_movk_i32 s60, 0x2c00
	s_movk_i32 s61, 0x5000
	s_mov_b32 s63, 0xb000
	s_mov_b32 s64, 0x1b000
	s_mov_b32 s65, 0x21000
	s_mov_b32 s66, 0x31000
	s_mov_b32 s67, 0x37000
	s_mov_b32 s68, 0x42000
	s_mov_b32 s69, 0x47000
	s_mov_b32 s70, 0x4d000
	s_mov_b32 s71, 0x52000
	s_mov_b32 s72, 0x58000
	s_mov_b32 s73, 0x5d000
	s_mov_b32 s74, 0x63000
	s_mov_b32 s76, 0x68000
	s_mov_b32 s77, 0x6e000
	s_mov_b32 s78, 0x73000
	s_mov_b32 s79, 0x79000
	s_mov_b32 s80, 0x7e000
	s_mov_b32 s81, 0x84000
	s_mov_b32 s82, 0x89000
	s_mov_b32 s83, 0x8f000
	s_mov_b32 s85, 0x94000
	s_mov_b32 s86, 0x9a000
	s_movk_i32 s87, 0x5120
	v_lshlrev_b32_e32 v10, 2, v2
	v_add_u32_e32 v45, 0x400, v13
	v_add_u32_e32 v46, 0x800, v13
	v_add_u32_e32 v47, 0xc00, v13
	v_add_u32_e32 v48, 0x1000, v13
	v_add_u32_e32 v49, 0x1400, v13
	v_add_u32_e32 v50, 0x1800, v13
	v_add_u32_e32 v51, 0x1c00, v13
	s_mov_b32 s88, s3
	s_branch .LBB0_9

; template <int MODE> __device__ __forceinline__ void phase0(KP P, LAS unsigned char* lds, int gw, int NGW, int wave, int lane) {
;     ...
;     if (MODE & 5) for (int it = ((MODE & 1) ? 0 : I1) + gw; it < ((MODE & 4) ? NIT : I1); it += NGW) {
;         int r = it;
.LBB0_8:
	s_add_i32 s88, s88, s62
	s_add_i32 s4, s4, s5
	s_add_i32 s18, s18, s19
	s_cmp_gt_i32 s88, s100
	s_cbranch_scc1 .LBB0_61

; #define GAS __attribute__((address_space(1)))
; template <int MODE> __device__ __forceinline__ void phase0(KP P, LAS unsigned char* lds, int gw, int NGW, int wave, int lane) {
;     ...
;     }
;     const GAS float* gm = ((const GAS float*)P->in[2]);
;     f32x4 gv[4];
; #pragma unroll
;     for (int j = 0; j < 4; ++j) gv[j] = *((const GAS f32x4*)gm + lane + 64 * j);
;     if (MODE & 2) for (int m0 = gw; m0 < TT; m0 += 2 * NGW) {
;         const int m1 = (m0 + NGW < TT) ? m0 + NGW : m0;
;         f32x4 v[2][4]; f32x4 pv[2]; float s[2] = {0.f, 0.f};
; #pragma unroll
;         for (int u = 0; u < 2; ++u) { const int m = u ? m1 : m0; const GAS f32x4* xr = (const GAS f32x4*)(((const GAS float*)P->in[0]) + (size_t)m * DM) + lane;
; #pragma unroll
;             for (int j = 0; j < 4; ++j) v[u][j] = __builtin_nontemporal_load(xr + 64 * j);
;             pv[u] = __builtin_nontemporal_load((const GAS f32x4*)(((const GAS float*)P->in[1]) + (size_t)m * 256) + lane); }
.LBB0_61:
	s_cmp_lg_u32 s101, 0
	s_cbranch_scc1 .Lp0_pass2_ret
	v_readlane_b32 s76, v248, 0
	s_cmpk_lt_i32 s3, 0x4000
	v_mbcnt_lo_u32_b32 v195, -1, 0
	v_readlane_b32 s77, v248, 1
	s_cbranch_scc0 .LBB0_64
	s_load_dwordx2 s[4:5], s[14:15], 0x10
	v_ashrrev_i32_e32 v19, 31, v18
	v_lshlrev_b64 v[22:23], 4, v[18:19]
	v_mbcnt_hi_u32_b32 v19, -1, v195
	v_and_b32_e32 v1, 64, v19
	s_waitcnt lgkmcnt(0)
	v_lshl_add_u64 v[20:21], s[4:5], 0, v[22:23]
	global_load_dwordx4 v[2:5], v[20:21], off
	global_load_dwordx4 v[6:9], v[20:21], off offset:1024
	global_load_dwordx4 v[10:13], v[20:21], off offset:2048
	global_load_dwordx4 v[14:17], v[20:21], off offset:3072
	v_add_u32_e32 v24, 64, v1
	v_xor_b32_e32 v1, 1, v19
	v_cmp_lt_i32_e32 vcc, v1, v24
	v_xor_b32_e32 v25, 2, v19
	s_load_dwordx4 s[8:11], s[14:15], 0x0
	v_cndmask_b32_e32 v1, v19, v1, vcc
	v_cmp_lt_i32_e32 vcc, v25, v24
	v_lshlrev_b32_e32 v18, 2, v18
	s_mov_b64 s[4:5], 0x2800000
	v_cndmask_b32_e32 v25, v19, v25, vcc
	v_lshlrev_b32_e32 v26, 2, v25
	v_xor_b32_e32 v25, 4, v19
	v_cmp_lt_i32_e32 vcc, v25, v24
	s_waitcnt lgkmcnt(0)
	v_lshl_add_u64 v[20:21], s[8:9], 0, v[22:23]
	v_lshl_add_u64 v[22:23], s[10:11], 0, v[22:23]
	v_cndmask_b32_e32 v25, v19, v25, vcc
	v_lshlrev_b32_e32 v27, 2, v25
	v_xor_b32_e32 v25, 8, v19
	v_cmp_lt_i32_e32 vcc, v25, v24
	v_lshlrev_b32_e32 v1, 2, v1
	v_mov_b32_e32 v31, 0x358637bd
	v_cndmask_b32_e32 v25, v19, v25, vcc
	v_lshlrev_b32_e32 v28, 2, v25
	v_xor_b32_e32 v25, 16, v19
	v_cmp_lt_i32_e32 vcc, v25, v24
	s_mov_b32 s8, s3
	s_nop 0
	v_cndmask_b32_e32 v25, v19, v25, vcc
	v_lshlrev_b32_e32 v29, 2, v25
	v_xor_b32_e32 v25, 32, v19
	v_cmp_lt_i32_e32 vcc, v25, v24
	s_nop 1
	v_cndmask_b32_e32 v19, v19, v25, vcc
	v_lshlrev_b32_e32 v30, 2, v19
	v_ashrrev_i32_e32 v19, 31, v18
	v_lshl_add_u64 v[24:25], v[18:19], 1, s[12:13]
	v_lshl_add_u64 v[18:19], v[24:25], 0, s[4:5]
	s_mov_b64 s[4:5], 0xf400000
	v_lshl_add_u64 v[24:25], v[24:25], 0, s[4:5]

; template <int MODE> __device__ __forceinline__ void phase0(KP P, LAS unsigned char* lds, int gw, int NGW, int wave, int lane) {
;     ...
;     if (MODE & 5) for (int it = ((MODE & 1) ? 0 : I1) + gw; it < ((MODE & 4) ? NIT : I1); it += NGW) {
;         int r = it;
;         if (r < I1) { const int kb = r / 168, grp = r % 168, pn = grp >> 3, g = grp & 7; int src0;
;             if (pn < 4) src0 = ((pn < 2) ? 0 : 512) + 64 * (4 * (pn & 1) + (g & 3)) + 32 * (g >> 2);
;             else if (pn < 8) src0 = 1024 + 256 * (pn - 4) + 32 * g;
;             else if (pn == 8) src0 = (g < 2) ? 2048 + 32 * g : 2112;
;             else if (pn < 13) src0 = (g < 4) ? 2120 + 128 * (pn - 9) + 32 * g : 2632 + 128 * (pn - 9) + 32 * (g - 4);
;             else src0 = 3144 + 256 * (pn - 13) + 32 * g;
;             tr_item(((const GAS float*)P->in[3]), INW, 64 * kb, src0, (GAS f16*)(ws + WS_W1T), 1024, 32 * grp, nullptr, scr, lane); continue; } r -= I1;
;         if (r < I2) { tr_item(((const GAS float*)P->in[10]), 1024, 64 * (r / 32), 32 * (r % 32), (GAS f16*)(ws + WS_WAOT), 512, 32 * (r % 32), nullptr, scr, lane); continue; } r -= I2;
;         if (r < I2) { tr_item(((const GAS float*)P->in[11]), 1024, 64 * (r / 32), 32 * (r % 32), (GAS f16*)(ws + WS_WCOT), 512, 32 * (r % 32), nullptr, scr, lane); continue; } r -= I2;
;         if (r < I4) { tr_item(((const GAS float*)P->in[12]), 1024, 64 * (r / 32), 32 * (r % 32), (GAS f16*)(ws + WS_WOUTT), 1024, 32 * (r % 32), nullptr, scr, lane); continue; } r -= I4;
;         if (r < I5) { const int kb = r / 176, grp = r % 176, j = grp >> 3, g = grp & 7;
;             tr_item((g < 4) ? ((const GAS float*)P->in[14]) : ((const GAS float*)P->in[15]), DFF, 64 * kb, 128 * j + 32 * (g & 3), (GAS f16*)(ws + WS_WGUT), 1024, 32 * grp, ((const GAS float*)P->in[13]), scr, lane); continue; } r -= I5;
;         if (r < I6) { tr_item(((const GAS float*)P->in[16]), 1024, 64 * (r / 32), 32 * (r % 32), (GAS f16*)(ws + WS_WDT), DFF, 32 * (r % 32), nullptr, scr, lane); continue; } r -= I6;
;         if (r < I7) { tr_item(((const GAS float*)P->in[18]), 1024, 64 * (r / 32), 32 * (r % 32), (GAS f16*)(ws + WS_WPGT), 1024, 32 * (r % 32), ((const GAS float*)P->in[17]), scr, lane); continue; } r -= I7;
;         tr_item(((const GAS float*)P->in[19]), 1024, 64 * (r / 32), 32 * (r % 32), (GAS f16*)(ws + WS_WPPT), 256, 32 * (r % 32), nullptr, scr, lane);
;     }
.LBB0_284:
	s_cmp_lt_u32 s2, 64
	s_cbranch_scc1 .Lp0_pass2_skip
	s_cmpk_lg_u32 s30, 0x100
	s_cbranch_scc1 .Lp0_pass2_skip
	v_writelane_b32 v250, s3, 0
	v_writelane_b32 v250, s10, 1
	v_writelane_b32 v250, s11, 2
	v_writelane_b32 v250, s20, 3
	v_writelane_b32 v250, s21, 4
	v_writelane_b32 v250, s22, 5
	v_writelane_b32 v250, s23, 6
	v_writelane_b32 v250, s24, 7
	v_writelane_b32 v250, s25, 8
	v_writelane_b32 v250, s26, 9
	v_writelane_b32 v250, s27, 10
	v_writelane_b32 v250, s34, 11
	v_writelane_b32 v250, s35, 12
	v_writelane_b32 v250, s42, 13
	v_writelane_b32 v250, s43, 14
	v_writelane_b32 v250, s46, 15
	v_writelane_b32 v250, s62, 16
	v_writelane_b32 v250, s63, 17
	v_writelane_b32 v250, s64, 18
	v_writelane_b32 v250, s65, 19
	v_writelane_b32 v250, s66, 20
	v_writelane_b32 v250, s67, 21
	v_writelane_b32 v250, s68, 22
	v_writelane_b32 v250, s74, 23
	v_writelane_b32 v250, s76, 24
	v_writelane_b32 v250, s77, 25
	v_writelane_b32 v250, s79, 26
	v_writelane_b32 v250, s80, 27
	v_mov_b32_e32 v251, v3
	s_mov_b32 s101, 1
	s_movk_i32 s100, 0x217f
	s_sub_i32 s3, s2, 64
	s_lshl_b32 s3, s3, 3
	s_add_i32 s3, s3, s84
	s_addk_i32 s3, 0xa80
	s_movk_i32 s62, 0x600
	s_mov_b64 s[14:15], s[0:1]
	v_mbcnt_lo_u32_b32 v18, -1, 0
	v_mbcnt_hi_u32_b32 v18, -1, v18
	s_load_dwordx2 s[12:13], s[14:15], 0xa8
	s_cmp_gt_i32 s3, s100
	s_cbranch_scc1 .Lp0_pass2_ret
	s_branch .Lp0_reenter
.Lp0_pass2_ret:
	s_waitcnt lgkmcnt(0)
	v_readlane_b32 s3, v250, 0
	v_readlane_b32 s10, v250, 1
	v_readlane_b32 s11, v250, 2
	v_readlane_b32 s20, v250, 3
	v_readlane_b32 s21, v250, 4
	v_readlane_b32 s22, v250, 5
	v_readlane_b32 s23, v250, 6
	v_readlane_b32 s24, v250, 7
	v_readlane_b32 s25, v250, 8
	v_readlane_b32 s26, v250, 9
	v_readlane_b32 s27, v250, 10
	v_readlane_b32 s34, v250, 11
	v_readlane_b32 s35, v250, 12
	v_readlane_b32 s42, v250, 13
	v_readlane_b32 s43, v250, 14
	v_readlane_b32 s46, v250, 15
	v_readlane_b32 s62, v250, 16
	v_readlane_b32 s63, v250, 17
	v_readlane_b32 s64, v250, 18
	v_readlane_b32 s65, v250, 19
	v_readlane_b32 s66, v250, 20
	v_readlane_b32 s67, v250, 21
	v_readlane_b32 s68, v250, 22
	v_readlane_b32 s74, v250, 23
	v_readlane_b32 s76, v250, 24
	v_readlane_b32 s77, v250, 25
	v_readlane_b32 s79, v250, 26
	v_readlane_b32 s80, v250, 27
	v_mov_b32_e32 v3, v251
	s_nop 4

; __global__ void __launch_bounds__(512) mega_fwd(Params P_) {
	.amdhsa_kernel _Z8mega_fwd6Params
		.amdhsa_group_segment_fixed_size 0
		.amdhsa_private_segment_fixed_size 0
		.amdhsa_kernarg_size 432
		.amdhsa_user_sgpr_count 2
		.amdhsa_user_sgpr_dispatch_ptr 0
		.amdhsa_user_sgpr_queue_ptr 0
		.amdhsa_user_sgpr_kernarg_segment_ptr 1
		.amdhsa_user_sgpr_dispatch_id 0
		.amdhsa_user_sgpr_kernarg_preload_length 0
		.amdhsa_user_sgpr_kernarg_preload_offset 0
		.amdhsa_user_sgpr_private_segment_size 0
		.amdhsa_uses_dynamic_stack 0
		.amdhsa_enable_private_segment 0
		.amdhsa_system_sgpr_workgroup_id_x 1
		.amdhsa_system_sgpr_workgroup_id_y 0
		.amdhsa_system_sgpr_workgroup_id_z 0
		.amdhsa_system_sgpr_workgroup_info 0
		.amdhsa_system_vgpr_workitem_id 2
		.amdhsa_next_free_vgpr 256
		.amdhsa_next_free_sgpr 102
		.amdhsa_accum_offset 256
		.amdhsa_reserve_vcc 1
		.amdhsa_float_round_mode_32 0
		.amdhsa_float_round_mode_16_64 0
		.amdhsa_float_denorm_mode_32 3
		.amdhsa_float_denorm_mode_16_64 3
		.amdhsa_dx10_clamp 1
		.amdhsa_ieee_mode 1
		.amdhsa_fp16_overflow 0
		.amdhsa_tg_split 0
		.amdhsa_exception_fp_ieee_invalid_op 0
		.amdhsa_exception_fp_denorm_src 0
		.amdhsa_exception_fp_ieee_div_zero 0
		.amdhsa_exception_fp_ieee_overflow 0
		.amdhsa_exception_fp_ieee_underflow 0
		.amdhsa_exception_fp_ieee_inexact 0
		.amdhsa_exception_int_div_zero 0
	.end_amdhsa_kernel

; __global__ void __launch_bounds__(512) mega_fwd(Params P_) {
amdhsa.kernels:
  - .agpr_count:     0
    .args:
      - .offset:         0
        .size:           176
        .value_kind:     by_value
      - .offset:         176
        .size:           4
        .value_kind:     hidden_block_count_x
      - .offset:         180
        .size:           4
        .value_kind:     hidden_block_count_y
      - .offset:         184
        .size:           4
        .value_kind:     hidden_block_count_z
      - .offset:         188
        .size:           2
        .value_kind:     hidden_group_size_x
      - .offset:         190
        .size:           2
        .value_kind:     hidden_group_size_y
      - .offset:         192
        .size:           2
        .value_kind:     hidden_group_size_z
      - .offset:         194
        .size:           2
        .value_kind:     hidden_remainder_x
      - .offset:         196
        .size:           2
        .value_kind:     hidden_remainder_y
      - .offset:         198
        .size:           2
        .value_kind:     hidden_remainder_z
      - .offset:         216
        .size:           8
        .value_kind:     hidden_global_offset_x
      - .offset:         224
        .size:           8
        .value_kind:     hidden_global_offset_y
      - .offset:         232
        .size:           8
        .value_kind:     hidden_global_offset_z
      - .offset:         240
        .size:           2
        .value_kind:     hidden_grid_dims
      - .offset:         264
        .size:           8
        .value_kind:     hidden_multigrid_sync_arg
      - .offset:         296
        .size:           4
        .value_kind:     hidden_dynamic_lds_size
    .group_segment_fixed_size: 0
    .kernarg_segment_align: 8
    .kernarg_segment_size: 432
    .language:       OpenCL C
    .language_version:
      - 2
      - 0
    .max_flat_workgroup_size: 512
    .name:           _Z8mega_fwd6Params
    .private_segment_fixed_size: 0
    .sgpr_count:     108
    .sgpr_spill_count: 14
    .symbol:         _Z8mega_fwd6Params.kd
    .uniform_work_group_size: 1
    .uses_dynamic_stack: false
    .vgpr_count:     256
    .vgpr_spill_count: 0
    .wavefront_size: 64
